# ple<4> epilogue: 14 of the 16 residual loads of a tile issued together up front
# baseline (speedup 1.0000x reference)
.LBB0_2547:
	v_mul_f32_e32 v0, 0xbfb8aa3b, v58
	v_exp_f32_e32 v0, v0
	s_load_dwordx2 s[14:15], s[2:3], 0x1c8
	s_lshl_b32 s0, s0, 7
	s_ashr_i32 s1, s0, 31
	v_add_f32_e32 v0, 1.0, v0
	v_rcp_f32_e32 v122, v0
	v_mul_f32_e32 v0, 0xbfb8aa3b, v59
	v_exp_f32_e32 v0, v0
	s_add_u32 s28, s18, s0
	s_addc_u32 s29, 0, s1
	s_lshl_b64 s[28:29], s[28:29], 9
	v_add_f32_e32 v0, 1.0, v0
	v_rcp_f32_e32 v123, v0
	v_mul_f32_e32 v0, 0xbfb8aa3b, v60
	v_exp_f32_e32 v0, v0
	s_waitcnt lgkmcnt(0)
	s_add_u32 s14, s14, s28
	s_addc_u32 s15, s15, s29
	s_load_dwordx2 s[28:29], s[2:3], 0x120
	v_add_f32_e32 v0, 1.0, v0
	v_rcp_f32_e32 v124, v0
	v_mul_f32_e32 v0, 0xbfb8aa3b, v61
	v_exp_f32_e32 v0, v0
	s_lshl_b64 s[12:13], s[12:13], 9
	v_mov_b32_e32 v68, v196
	s_waitcnt lgkmcnt(0)
	s_add_u32 s12, s28, s12
	s_addc_u32 s13, s29, s13
	v_readfirstlane_b32 s1, v68
	s_ashr_i32 s28, s1, 6
	v_bfe_u32 v58, v68, 3, 3
	v_add_f32_e32 v0, 1.0, v0
	s_and_b32 s29, s28, 1
	v_lshl_or_b32 v58, s28, 3, v58
	v_rcp_f32_e32 v125, v0
	v_bfe_u32 v70, v68, 4, 2
	v_and_b32_e32 v0, 7, v68
	s_lshl_b32 s30, s29, 2
	v_ashrrev_i32_e32 v59, 31, v58
	v_bitop3_b32 v0, s30, v0, v70 bitop3:0x36
	v_lshlrev_b64 v[58:59], 9, v[58:59]
	v_lshl_add_u64 v[60:61], s[14:15], 0, v[58:59]
	v_lshlrev_b32_e32 v0, 4, v0
	s_lshl_b32 s38, s28, 10
	v_lshl_add_u64 v[60:61], v[60:61], 0, v[0:1]
	s_mov_b32 m0, s38
	s_mov_b64 s[14:15], 0x4000
	s_add_i32 s31, s38, 0x1000
	v_lshl_add_u64 v[58:59], s[12:13], 0, v[58:59]
	s_waitcnt vmcnt(0)
	s_barrier
	global_load_lds_dwordx4 v[60:61], off
	v_lshl_add_u64 v[66:67], v[60:61], 0, s[14:15]
	s_mov_b32 m0, s31
	s_mov_b64 s[12:13], 0x8000
	s_add_i32 s33, s38, 0x2000
	global_load_lds_dwordx4 v[66:67], off
	v_lshl_add_u64 v[66:67], v[60:61], 0, s[12:13]
	s_mov_b32 m0, s33
	s_mov_b64 s[40:41], 0xc000
	s_add_i32 s34, s38, 0x3000
	global_load_lds_dwordx4 v[66:67], off
	v_lshl_add_u64 v[66:67], v[60:61], 0, s[40:41]
	s_mov_b32 m0, s34
	s_add_i32 s35, s38, 0x4000
	v_lshl_add_u64 v[58:59], v[58:59], 0, v[0:1]
	global_load_lds_dwordx4 v[66:67], off
	s_mov_b32 m0, s35
	s_add_i32 s36, s38, 0x5000
	global_load_lds_dwordx4 v[58:59], off
	v_lshl_add_u64 v[66:67], v[58:59], 0, s[14:15]
	s_mov_b32 m0, s36
	s_add_i32 s37, s38, 0x6000
	global_load_lds_dwordx4 v[66:67], off
	v_lshl_add_u64 v[66:67], v[58:59], 0, s[12:13]
	s_mov_b32 m0, s37
	s_add_i32 s39, s38, 0x7000
	s_lshr_b32 s1, s1, 1
	v_and_b32_e32 v69, 15, v68
	global_load_lds_dwordx4 v[66:67], off
	v_lshl_add_u64 v[66:67], v[58:59], 0, s[40:41]
	s_mov_b32 m0, s39
	v_bfe_u32 v0, v68, 1, 3
	s_and_b32 s1, s1, 0x1ffffc0
	global_load_lds_dwordx4 v[66:67], off
	v_or_b32_e32 v66, s1, v69
	v_lshlrev_b32_e32 v67, 7, v69
	v_xor_b32_e32 v71, v70, v0
	v_bitop3_b32 v0, v70, v0, 4 bitop3:0x36
	v_lshlrev_b32_e32 v66, 7, v66
	v_lshl_or_b32 v67, s29, 13, v67
	s_add_i32 s29, s38, 0x8a00
	v_lshlrev_b32_e32 v71, 4, v71
	v_lshlrev_b32_e32 v0, 4, v0
	v_add_u32_e32 v68, 0x8a00, v66
	v_add_u32_e32 v69, 0x8a00, v67
	s_add_i32 s30, s38, 0x9a00
	v_or_b32_e32 v133, v66, v71
	v_or_b32_e32 v170, v67, v71
	v_or_b32_e32 v171, v66, v0
	v_or_b32_e32 v182, v67, v0
	v_lshl_add_u64 v[66:67], v[60:61], 0, s[46:47]
	s_mov_b32 m0, s29
	s_mov_b64 s[40:41], 0x4080
	s_add_i32 s28, s38, 0xaa00
	s_waitcnt vmcnt(0)
	s_waitcnt vmcnt(0) lgkmcnt(0)
	s_barrier
	global_load_lds_dwordx4 v[66:67], off
	v_lshl_add_u64 v[66:67], v[60:61], 0, s[40:41]
	s_mov_b32 m0, s30
	s_add_i32 s15, s38, 0xba00
	global_load_lds_dwordx4 v[66:67], off
	v_lshl_add_u64 v[66:67], v[60:61], 0, s[60:61]
	s_mov_b32 m0, s28
	s_mov_b64 s[42:43], 0xc080
	s_add_i32 s1, s38, 0xca00
	global_load_lds_dwordx4 v[66:67], off
	v_lshl_add_u64 v[66:67], v[60:61], 0, s[42:43]
	s_mov_b32 m0, s15
	s_add_i32 s14, s38, 0xda00
	global_load_lds_dwordx4 v[66:67], off
	v_lshl_add_u64 v[66:67], v[58:59], 0, s[46:47]
	s_mov_b32 m0, s1
	s_add_i32 s13, s38, 0xea00
	global_load_lds_dwordx4 v[66:67], off
	v_lshl_add_u64 v[66:67], v[58:59], 0, s[40:41]
	s_mov_b32 m0, s14
	s_add_i32 s12, s38, 0xfa00
	global_load_lds_dwordx4 v[66:67], off
	v_lshl_add_u64 v[66:67], v[58:59], 0, s[60:61]
	s_mov_b32 m0, s13
	v_or_b32_e32 v183, v68, v71
	global_load_lds_dwordx4 v[66:67], off
	v_lshl_add_u64 v[66:67], v[58:59], 0, s[42:43]
	s_mov_b32 m0, s12
	v_or_b32_e32 v184, v69, v71
	global_load_lds_dwordx4 v[66:67], off
	v_or_b32_e32 v185, v68, v0
	v_or_b32_e32 v0, v69, v0
	ds_read_b128 v[66:69], v133
	ds_read_b128 v[70:73], v133 offset:2048
	ds_read_b128 v[74:77], v133 offset:4096
	ds_read_b128 v[78:81], v133 offset:6144
	ds_read_b128 v[82:85], v170 offset:16384
	ds_read_b128 v[86:89], v170 offset:18432
	ds_read_b128 v[90:93], v170 offset:20480
	ds_read_b128 v[94:97], v170 offset:22528
	s_setprio 1
	s_waitcnt lgkmcnt(0)
	v_mfma_f32_16x16x32_bf16 v[98:101], v[82:85], v[66:69], 0
	v_mfma_f32_16x16x32_bf16 v[102:105], v[86:89], v[66:69], 0
	v_mfma_f32_16x16x32_bf16 v[106:109], v[90:93], v[66:69], 0
	v_mfma_f32_16x16x32_bf16 v[66:69], v[94:97], v[66:69], 0
	v_mfma_f32_16x16x32_bf16 v[110:113], v[82:85], v[70:73], 0
	v_mfma_f32_16x16x32_bf16 v[114:117], v[86:89], v[70:73], 0
	v_mfma_f32_16x16x32_bf16 v[118:121], v[90:93], v[70:73], 0
	v_mfma_f32_16x16x32_bf16 v[70:73], v[94:97], v[70:73], 0
	v_mfma_f32_16x16x32_bf16 v[126:129], v[82:85], v[74:77], 0
	v_mfma_f32_16x16x32_bf16 v[136:139], v[86:89], v[74:77], 0
	v_mfma_f32_16x16x32_bf16 v[142:145], v[90:93], v[74:77], 0
	v_mfma_f32_16x16x32_bf16 v[74:77], v[94:97], v[74:77], 0
	v_mfma_f32_16x16x32_bf16 v[82:85], v[82:85], v[78:81], 0
	v_mfma_f32_16x16x32_bf16 v[86:89], v[86:89], v[78:81], 0
	v_mfma_f32_16x16x32_bf16 v[90:93], v[90:93], v[78:81], 0
	v_mfma_f32_16x16x32_bf16 v[78:81], v[94:97], v[78:81], 0
	s_setprio 0
	ds_read_b128 v[94:97], v171
	ds_read_b128 v[146:149], v171 offset:2048
	ds_read_b128 v[150:153], v171 offset:4096
	ds_read_b128 v[154:157], v171 offset:6144
	ds_read_b128 v[158:161], v182 offset:16384
	ds_read_b128 v[162:165], v182 offset:18432
	ds_read_b128 v[166:169], v182 offset:20480
	ds_read_b128 v[174:177], v182 offset:22528
	s_setprio 1
	s_waitcnt lgkmcnt(0)
	v_mfma_f32_16x16x32_bf16 v[98:101], v[158:161], v[94:97], v[98:101]
	v_mfma_f32_16x16x32_bf16 v[102:105], v[162:165], v[94:97], v[102:105]
	v_mfma_f32_16x16x32_bf16 v[106:109], v[166:169], v[94:97], v[106:109]
	v_mfma_f32_16x16x32_bf16 v[66:69], v[174:177], v[94:97], v[66:69]
	v_mfma_f32_16x16x32_bf16 v[94:97], v[158:161], v[146:149], v[110:113]
	v_mfma_f32_16x16x32_bf16 v[110:113], v[162:165], v[146:149], v[114:117]
	v_mfma_f32_16x16x32_bf16 v[114:117], v[166:169], v[146:149], v[118:121]
	v_mfma_f32_16x16x32_bf16 v[70:73], v[174:177], v[146:149], v[70:73]
	v_mfma_f32_16x16x32_bf16 v[118:121], v[158:161], v[150:153], v[126:129]
	v_mfma_f32_16x16x32_bf16 v[126:129], v[162:165], v[150:153], v[136:139]
	v_mfma_f32_16x16x32_bf16 v[136:139], v[166:169], v[150:153], v[142:145]
	v_mfma_f32_16x16x32_bf16 v[74:77], v[174:177], v[150:153], v[74:77]
	v_mfma_f32_16x16x32_bf16 v[82:85], v[158:161], v[154:157], v[82:85]
	v_mfma_f32_16x16x32_bf16 v[86:89], v[162:165], v[154:157], v[86:89]
	v_mfma_f32_16x16x32_bf16 v[90:93], v[166:169], v[154:157], v[90:93]
	v_mfma_f32_16x16x32_bf16 v[78:81], v[174:177], v[154:157], v[78:81]
	s_setprio 0
	s_mov_b32 m0, s38
	v_lshl_add_u64 v[142:143], v[60:61], 0, s[62:63]
	s_mov_b64 s[42:43], 0x4100
	s_waitcnt vmcnt(0)
	s_waitcnt vmcnt(0)
	s_barrier
	v_lshl_add_u64 v[154:155], v[60:61], 0, s[42:43]
	global_load_lds_dwordx4 v[142:143], off
	s_mov_b32 m0, s31
	s_mov_b64 s[40:41], 0xc100
	v_lshl_add_u64 v[152:153], v[60:61], 0, s[56:57]
	global_load_lds_dwordx4 v[154:155], off
	s_mov_b32 m0, s33
	v_lshl_add_u64 v[150:151], v[60:61], 0, s[40:41]
	global_load_lds_dwordx4 v[152:153], off
	s_mov_b32 m0, s34
	v_lshl_add_u64 v[130:131], v[58:59], 0, s[62:63]
	global_load_lds_dwordx4 v[150:151], off
	s_mov_b32 m0, s35
	v_lshl_add_u64 v[148:149], v[58:59], 0, s[42:43]
	global_load_lds_dwordx4 v[130:131], off
	s_mov_b32 m0, s36
	v_lshl_add_u64 v[146:147], v[58:59], 0, s[56:57]
	global_load_lds_dwordx4 v[148:149], off
	s_mov_b32 m0, s37
	v_lshl_add_u64 v[144:145], v[58:59], 0, s[40:41]
	global_load_lds_dwordx4 v[146:147], off
	s_mov_b32 m0, s39
	s_nop 0
	global_load_lds_dwordx4 v[144:145], off
	ds_read_b128 v[142:145], v183
	ds_read_b128 v[146:149], v183 offset:2048
	ds_read_b128 v[150:153], v183 offset:4096
	ds_read_b128 v[154:157], v183 offset:6144
	ds_read_b128 v[158:161], v184 offset:16384
	ds_read_b128 v[162:165], v184 offset:18432
	ds_read_b128 v[166:169], v184 offset:20480
	ds_read_b128 v[174:177], v184 offset:22528
	s_setprio 1
	s_waitcnt lgkmcnt(0)
	v_mfma_f32_16x16x32_bf16 v[98:101], v[158:161], v[142:145], v[98:101]
	v_mfma_f32_16x16x32_bf16 v[102:105], v[162:165], v[142:145], v[102:105]
	v_mfma_f32_16x16x32_bf16 v[106:109], v[166:169], v[142:145], v[106:109]
	v_mfma_f32_16x16x32_bf16 v[66:69], v[174:177], v[142:145], v[66:69]
	v_mfma_f32_16x16x32_bf16 v[94:97], v[158:161], v[146:149], v[94:97]
	v_mfma_f32_16x16x32_bf16 v[110:113], v[162:165], v[146:149], v[110:113]
	v_mfma_f32_16x16x32_bf16 v[114:117], v[166:169], v[146:149], v[114:117]
	v_mfma_f32_16x16x32_bf16 v[70:73], v[174:177], v[146:149], v[70:73]
	v_mfma_f32_16x16x32_bf16 v[118:121], v[158:161], v[150:153], v[118:121]
	v_mfma_f32_16x16x32_bf16 v[126:129], v[162:165], v[150:153], v[126:129]
	v_mfma_f32_16x16x32_bf16 v[136:139], v[166:169], v[150:153], v[136:139]
	v_mfma_f32_16x16x32_bf16 v[74:77], v[174:177], v[150:153], v[74:77]
	v_mfma_f32_16x16x32_bf16 v[82:85], v[158:161], v[154:157], v[82:85]
	v_mfma_f32_16x16x32_bf16 v[86:89], v[162:165], v[154:157], v[86:89]
	v_mfma_f32_16x16x32_bf16 v[90:93], v[166:169], v[154:157], v[90:93]
	v_mfma_f32_16x16x32_bf16 v[78:81], v[174:177], v[154:157], v[78:81]
	s_setprio 0
	ds_read_b128 v[142:145], v185
	ds_read_b128 v[146:149], v185 offset:2048
	ds_read_b128 v[150:153], v185 offset:4096
	ds_read_b128 v[154:157], v185 offset:6144
	ds_read_b128 v[158:161], v0 offset:16384
	ds_read_b128 v[162:165], v0 offset:18432
	ds_read_b128 v[166:169], v0 offset:20480
	ds_read_b128 v[174:177], v0 offset:22528
	s_setprio 1
	s_waitcnt lgkmcnt(0)
	v_mfma_f32_16x16x32_bf16 v[98:101], v[158:161], v[142:145], v[98:101]
	v_mfma_f32_16x16x32_bf16 v[102:105], v[162:165], v[142:145], v[102:105]
	v_mfma_f32_16x16x32_bf16 v[106:109], v[166:169], v[142:145], v[106:109]
	v_mfma_f32_16x16x32_bf16 v[66:69], v[174:177], v[142:145], v[66:69]
	v_mfma_f32_16x16x32_bf16 v[94:97], v[158:161], v[146:149], v[94:97]
	v_mfma_f32_16x16x32_bf16 v[110:113], v[162:165], v[146:149], v[110:113]
	v_mfma_f32_16x16x32_bf16 v[114:117], v[166:169], v[146:149], v[114:117]
	v_mfma_f32_16x16x32_bf16 v[70:73], v[174:177], v[146:149], v[70:73]
	v_mfma_f32_16x16x32_bf16 v[118:121], v[158:161], v[150:153], v[118:121]
	v_mfma_f32_16x16x32_bf16 v[126:129], v[162:165], v[150:153], v[126:129]
	v_mfma_f32_16x16x32_bf16 v[136:139], v[166:169], v[150:153], v[136:139]
	v_mfma_f32_16x16x32_bf16 v[74:77], v[174:177], v[150:153], v[74:77]
	v_mfma_f32_16x16x32_bf16 v[82:85], v[158:161], v[154:157], v[82:85]
	v_mfma_f32_16x16x32_bf16 v[86:89], v[162:165], v[154:157], v[86:89]
	v_mfma_f32_16x16x32_bf16 v[90:93], v[166:169], v[154:157], v[90:93]
	v_mfma_f32_16x16x32_bf16 v[78:81], v[174:177], v[154:157], v[78:81]
	s_setprio 0
	s_mov_b64 s[34:35], 0x180
	s_mov_b32 m0, s29
	v_lshl_add_u64 v[130:131], v[60:61], 0, s[34:35]
	s_mov_b64 s[36:37], 0x4180
	s_waitcnt vmcnt(0)
	s_waitcnt vmcnt(0)
	s_barrier
	global_load_lds_dwordx4 v[130:131], off
	v_lshl_add_u64 v[130:131], v[60:61], 0, s[36:37]
	s_mov_b32 m0, s30
	s_mov_b64 s[30:31], 0x8180
	global_load_lds_dwordx4 v[130:131], off
	v_lshl_add_u64 v[130:131], v[60:61], 0, s[30:31]
	s_mov_b32 m0, s28
	s_mov_b64 s[28:29], 0xc180
	global_load_lds_dwordx4 v[130:131], off
	v_lshl_add_u64 v[60:61], v[60:61], 0, s[28:29]
	s_mov_b32 m0, s15
	s_nop 0
	global_load_lds_dwordx4 v[60:61], off
	v_lshl_add_u64 v[60:61], v[58:59], 0, s[34:35]
	s_mov_b32 m0, s1
	s_nop 0
	global_load_lds_dwordx4 v[60:61], off
	v_lshl_add_u64 v[60:61], v[58:59], 0, s[36:37]
	s_mov_b32 m0, s14
	s_nop 0
	global_load_lds_dwordx4 v[60:61], off
	v_lshl_add_u64 v[60:61], v[58:59], 0, s[30:31]
	s_mov_b32 m0, s13
	v_lshl_add_u64 v[58:59], v[58:59], 0, s[28:29]
	global_load_lds_dwordx4 v[60:61], off
	s_mov_b32 m0, s12
	s_nop 0
	global_load_lds_dwordx4 v[58:59], off
	ds_read_b128 v[58:61], v133
	ds_read_b128 v[142:145], v133 offset:2048
	ds_read_b128 v[146:149], v133 offset:4096
	ds_read_b128 v[150:153], v133 offset:6144
	ds_read_b128 v[154:157], v170 offset:16384
	ds_read_b128 v[158:161], v170 offset:18432
	ds_read_b128 v[162:165], v170 offset:20480
	ds_read_b128 v[166:169], v170 offset:22528
	s_setprio 1
	s_waitcnt lgkmcnt(0)
	v_mfma_f32_16x16x32_bf16 v[98:101], v[154:157], v[58:61], v[98:101]
	v_mfma_f32_16x16x32_bf16 v[102:105], v[158:161], v[58:61], v[102:105]
	v_mfma_f32_16x16x32_bf16 v[106:109], v[162:165], v[58:61], v[106:109]
	v_mfma_f32_16x16x32_bf16 v[58:61], v[166:169], v[58:61], v[66:69]
	v_mfma_f32_16x16x32_bf16 v[66:69], v[154:157], v[142:145], v[94:97]
	v_mfma_f32_16x16x32_bf16 v[94:97], v[158:161], v[142:145], v[110:113]
	v_mfma_f32_16x16x32_bf16 v[110:113], v[162:165], v[142:145], v[114:117]
	v_mfma_f32_16x16x32_bf16 v[70:73], v[166:169], v[142:145], v[70:73]
	v_mfma_f32_16x16x32_bf16 v[114:117], v[154:157], v[146:149], v[118:121]
	v_mfma_f32_16x16x32_bf16 v[118:121], v[158:161], v[146:149], v[126:129]
	v_mfma_f32_16x16x32_bf16 v[126:129], v[162:165], v[146:149], v[136:139]
	v_mfma_f32_16x16x32_bf16 v[74:77], v[166:169], v[146:149], v[74:77]
	v_mfma_f32_16x16x32_bf16 v[82:85], v[154:157], v[150:153], v[82:85]
	v_mfma_f32_16x16x32_bf16 v[86:89], v[158:161], v[150:153], v[86:89]
	v_mfma_f32_16x16x32_bf16 v[90:93], v[162:165], v[150:153], v[90:93]
	v_mfma_f32_16x16x32_bf16 v[78:81], v[166:169], v[150:153], v[78:81]
	s_setprio 0
	ds_read_b128 v[136:139], v171
	ds_read_b128 v[142:145], v171 offset:2048
	ds_read_b128 v[146:149], v171 offset:4096
	ds_read_b128 v[150:153], v171 offset:6144
	ds_read_b128 v[154:157], v182 offset:16384
	ds_read_b128 v[158:161], v182 offset:18432
	ds_read_b128 v[162:165], v182 offset:20480
	ds_read_b128 v[166:169], v182 offset:22528
	s_setprio 1
	s_waitcnt lgkmcnt(0)
	v_mfma_f32_16x16x32_bf16 v[98:101], v[154:157], v[136:139], v[98:101]
	v_mfma_f32_16x16x32_bf16 v[102:105], v[158:161], v[136:139], v[102:105]
	v_mfma_f32_16x16x32_bf16 v[106:109], v[162:165], v[136:139], v[106:109]
	v_mfma_f32_16x16x32_bf16 v[58:61], v[166:169], v[136:139], v[58:61]
	v_mfma_f32_16x16x32_bf16 v[66:69], v[154:157], v[142:145], v[66:69]
	v_mfma_f32_16x16x32_bf16 v[94:97], v[158:161], v[142:145], v[94:97]
	v_mfma_f32_16x16x32_bf16 v[110:113], v[162:165], v[142:145], v[110:113]
	v_mfma_f32_16x16x32_bf16 v[70:73], v[166:169], v[142:145], v[70:73]
	v_mfma_f32_16x16x32_bf16 v[114:117], v[154:157], v[146:149], v[114:117]
	v_mfma_f32_16x16x32_bf16 v[118:121], v[158:161], v[146:149], v[118:121]
	v_mfma_f32_16x16x32_bf16 v[126:129], v[162:165], v[146:149], v[126:129]
	v_mfma_f32_16x16x32_bf16 v[74:77], v[166:169], v[146:149], v[74:77]
	v_mfma_f32_16x16x32_bf16 v[82:85], v[154:157], v[150:153], v[82:85]
	v_mfma_f32_16x16x32_bf16 v[86:89], v[158:161], v[150:153], v[86:89]
	v_mfma_f32_16x16x32_bf16 v[90:93], v[162:165], v[150:153], v[90:93]
	v_mfma_f32_16x16x32_bf16 v[78:81], v[166:169], v[150:153], v[78:81]
	s_setprio 0
	s_waitcnt vmcnt(0)
	s_waitcnt vmcnt(0)
	s_barrier
	ds_read_b128 v[136:139], v184 offset:22528
	ds_read_b128 v[142:145], v184 offset:20480
	ds_read_b128 v[146:149], v184 offset:18432
	ds_read_b128 v[150:153], v184 offset:16384
	ds_read_b128 v[154:157], v183 offset:6144
	ds_read_b128 v[158:161], v183 offset:4096
	ds_read_b128 v[162:165], v183 offset:2048
	ds_read_b128 v[166:169], v183
	s_setprio 1
	s_waitcnt lgkmcnt(0)
	v_mfma_f32_16x16x32_bf16 v[98:101], v[150:153], v[166:169], v[98:101]
	v_mfma_f32_16x16x32_bf16 v[102:105], v[146:149], v[166:169], v[102:105]
	v_mfma_f32_16x16x32_bf16 v[106:109], v[142:145], v[166:169], v[106:109]
	v_mfma_f32_16x16x32_bf16 v[58:61], v[136:139], v[166:169], v[58:61]
	v_mfma_f32_16x16x32_bf16 v[66:69], v[150:153], v[162:165], v[66:69]
	v_mfma_f32_16x16x32_bf16 v[94:97], v[146:149], v[162:165], v[94:97]
	v_mfma_f32_16x16x32_bf16 v[70:73], v[136:139], v[162:165], v[70:73]
	v_mfma_f32_16x16x32_bf16 v[126:129], v[142:145], v[158:161], v[126:129]
	v_mfma_f32_16x16x32_bf16 v[74:77], v[136:139], v[158:161], v[74:77]
	v_mfma_f32_16x16x32_bf16 v[136:139], v[136:139], v[154:157], v[78:81]
	v_mfma_f32_16x16x32_bf16 v[166:169], v[142:145], v[162:165], v[110:113]
	v_mfma_f32_16x16x32_bf16 v[162:165], v[150:153], v[158:161], v[114:117]
	v_mfma_f32_16x16x32_bf16 v[174:177], v[146:149], v[158:161], v[118:121]
	v_mfma_f32_16x16x32_bf16 v[150:153], v[150:153], v[154:157], v[82:85]
	v_mfma_f32_16x16x32_bf16 v[146:149], v[146:149], v[154:157], v[86:89]
	v_mfma_f32_16x16x32_bf16 v[142:145], v[142:145], v[154:157], v[90:93]
	s_setprio 0
	ds_read_b128 v[78:81], v185
	ds_read_b128 v[82:85], v185 offset:2048
	ds_read_b128 v[154:157], v185 offset:4096
	ds_read_b128 v[158:161], v185 offset:6144
	ds_read_b128 v[182:185], v0 offset:16384
	ds_read_b128 v[188:191], v0 offset:18432
	ds_read_b128 v[192:195], v0 offset:20480
	ds_read_b128 v[206:209], v0 offset:22528
	s_setprio 1
	s_waitcnt lgkmcnt(3)
	v_mfma_f32_16x16x32_bf16 v[210:213], v[182:185], v[78:81], v[98:101]
	s_waitcnt lgkmcnt(2)
	v_mfma_f32_16x16x32_bf16 v[118:121], v[188:191], v[78:81], v[102:105]
	s_waitcnt lgkmcnt(1)
	v_mfma_f32_16x16x32_bf16 v[114:117], v[192:195], v[78:81], v[106:109]
	s_waitcnt lgkmcnt(0)
	v_mfma_f32_16x16x32_bf16 v[110:113], v[206:209], v[78:81], v[58:61]
	v_mfma_f32_16x16x32_bf16 v[106:109], v[182:185], v[82:85], v[66:69]
	v_mfma_f32_16x16x32_bf16 v[102:105], v[188:191], v[82:85], v[94:97]
	v_mfma_f32_16x16x32_bf16 v[98:101], v[192:195], v[82:85], v[166:169]
	v_mfma_f32_16x16x32_bf16 v[94:97], v[206:209], v[82:85], v[70:73]
	v_mfma_f32_16x16x32_bf16 v[90:93], v[182:185], v[154:157], v[162:165]
	v_mfma_f32_16x16x32_bf16 v[86:89], v[188:191], v[154:157], v[174:177]
	v_mfma_f32_16x16x32_bf16 v[82:85], v[192:195], v[154:157], v[126:129]
	v_mfma_f32_16x16x32_bf16 v[78:81], v[206:209], v[154:157], v[74:77]
	v_mfma_f32_16x16x32_bf16 v[74:77], v[182:185], v[158:161], v[150:153]
	v_mfma_f32_16x16x32_bf16 v[70:73], v[188:191], v[158:161], v[146:149]
	v_mfma_f32_16x16x32_bf16 v[66:69], v[192:195], v[158:161], v[142:145]
	v_mfma_f32_16x16x32_bf16 v[58:61], v[206:209], v[158:161], v[136:139]
	s_setprio 0
	v_add_u32_e32 v128, s0, v140
	s_load_dwordx2 s[0:1], s[2:3], 0x130
	v_or_b32_e32 v126, s27, v141
	v_ashrrev_i32_e32 v127, 31, v126
	v_ashrrev_i32_e32 v129, 31, v128
	v_lshlrev_b64 v[136:137], 12, v[128:129]
	s_waitcnt lgkmcnt(0)
	v_lshl_add_u64 v[130:131], v[126:127], 2, s[0:1]
	v_lshl_add_u64 v[136:137], v[130:131], 0, v[136:137]
	v_add_co_u32_e32 v222, vcc, 0x10000, v136
	v_addc_co_u32_e32 v223, vcc, 0, v137, vcc
	v_add_co_u32_e32 v226, vcc, 0x20000, v136
	v_addc_co_u32_e32 v227, vcc, 0, v137, vcc
	v_add_co_u32_e32 v170, vcc, 0x30000, v136
	v_addc_co_u32_e32 v171, vcc, 0, v137, vcc
	global_load_dwordx4 v[146:149], v[136:137], off offset:64
	global_load_dwordx4 v[150:153], v[136:137], off offset:128
	global_load_dwordx4 v[154:157], v[136:137], off offset:192
	global_load_dwordx4 v[158:161], v[222:223], off
	global_load_dwordx4 v[162:165], v[222:223], off offset:64
	global_load_dwordx4 v[166:169], v[222:223], off offset:128
	global_load_dwordx4 v[174:177], v[222:223], off offset:192
	global_load_dwordx4 v[182:185], v[226:227], off
	global_load_dwordx4 v[188:191], v[226:227], off offset:64
	global_load_dwordx4 v[192:195], v[226:227], off offset:128
	global_load_dwordx4 v[206:209], v[226:227], off offset:192
	global_load_dwordx4 v[214:217], v[170:171], off
	global_load_dwordx4 v[218:221], v[170:171], off offset:64
	global_load_dwordx4 v[242:245], v[170:171], off offset:128
	global_load_dwordx4 v[142:145], v[136:137], off
	v_readlane_b32 s12, v250, 10
	v_readlane_b32 s13, v250, 11
	v_lshlrev_b64 v[138:139], 10, v[128:129]
	s_andn2_b64 vcc, exec, s[12:13]
	v_cndmask_b32_e64 v0, 0, 1, s[12:13]
	v_cmp_ne_u32_e64 s[0:1], 1, v0
	s_mov_b64 s[12:13], -1
	s_waitcnt vmcnt(0)
	v_pk_fma_f32 v[124:125], v[124:125], v[212:213], v[144:145]
	v_pk_fma_f32 v[122:123], v[122:123], v[210:211], v[142:143]
	s_cbranch_vccnz .LBB0_2549
	s_load_dwordx2 s[12:13], s[2:3], 0xd8
	s_waitcnt lgkmcnt(0)
	v_lshl_add_u64 v[142:143], v[138:139], 2, s[12:13]
	v_lshl_add_u64 v[142:143], v[126:127], 2, v[142:143]
	s_mov_b64 s[12:13], 0
	global_store_dwordx4 v[142:143], v[122:125], off nt

.LBB0_2551:
	s_nop 3
	v_mov_b32_e32 v122, v146
	v_mov_b32_e32 v123, v147
	v_mov_b32_e32 v124, v148
	v_mov_b32_e32 v125, v149
	v_mul_f32_e32 v0, 0xbfb8aa3b, v62
	v_mul_f32_e32 v62, 0xbfb8aa3b, v63
	v_mul_f32_e32 v63, 0xbfb8aa3b, v64
	v_mul_f32_e32 v64, 0xbfb8aa3b, v65
	v_exp_f32_e32 v0, v0
	v_exp_f32_e32 v62, v62
	v_exp_f32_e32 v63, v63
	v_exp_f32_e32 v64, v64
	v_add_f32_e32 v0, 1.0, v0
	v_add_f32_e32 v129, 1.0, v62
	v_add_f32_e32 v63, 1.0, v63
	v_add_f32_e32 v65, 1.0, v64
	v_rcp_f32_e32 v62, v0
	v_rcp_f32_e32 v64, v63
	v_rcp_f32_e32 v65, v65
	v_rcp_f32_e32 v63, v129
	s_and_b64 vcc, exec, s[0:1]
	s_mov_b64 s[12:13], -1
	v_pk_fma_f32 v[64:65], v[64:65], v[120:121], v[124:125]
	v_pk_fma_f32 v[62:63], v[62:63], v[118:119], v[122:123]
	s_cbranch_vccnz .LBB0_2553
	s_load_dwordx2 s[12:13], s[2:3], 0xd8
	s_waitcnt lgkmcnt(0)
	v_lshl_add_u64 v[118:119], v[138:139], 2, s[12:13]
	v_lshl_add_u64 v[118:119], v[126:127], 2, v[118:119]
	s_mov_b64 s[12:13], 0
	global_store_dwordx4 v[118:119], v[62:65], off offset:64 nt

.LBB0_2555:
	s_nop 3
	v_mov_b32_e32 v62, v150
	v_mov_b32_e32 v63, v151
	v_mov_b32_e32 v64, v152
	v_mov_b32_e32 v65, v153
	v_mul_f32_e32 v0, 0xbfb8aa3b, v54
	v_mul_f32_e32 v54, 0xbfb8aa3b, v55
	v_mul_f32_e32 v55, 0xbfb8aa3b, v56
	v_mul_f32_e32 v56, 0xbfb8aa3b, v57
	v_exp_f32_e32 v0, v0
	v_exp_f32_e32 v54, v54
	v_exp_f32_e32 v55, v55
	v_exp_f32_e32 v56, v56
	v_add_f32_e32 v0, 1.0, v0
	v_add_f32_e32 v118, 1.0, v54
	v_add_f32_e32 v55, 1.0, v55
	v_add_f32_e32 v57, 1.0, v56
	v_rcp_f32_e32 v54, v0
	v_rcp_f32_e32 v56, v55
	v_rcp_f32_e32 v57, v57
	v_rcp_f32_e32 v55, v118
	s_and_b64 vcc, exec, s[0:1]
	s_mov_b64 s[12:13], -1
	v_pk_fma_f32 v[56:57], v[56:57], v[116:117], v[64:65]
	v_pk_fma_f32 v[54:55], v[54:55], v[114:115], v[62:63]
	s_cbranch_vccnz .LBB0_2557
	s_load_dwordx2 s[12:13], s[2:3], 0xd8
	s_waitcnt lgkmcnt(0)
	v_lshl_add_u64 v[62:63], v[138:139], 2, s[12:13]
	v_lshl_add_u64 v[62:63], v[126:127], 2, v[62:63]
	s_mov_b64 s[12:13], 0
	global_store_dwordx4 v[62:63], v[54:57], off offset:128 nt

.LBB0_2559:
	s_nop 3
	v_mov_b32_e32 v54, v154
	v_mov_b32_e32 v55, v155
	v_mov_b32_e32 v56, v156
	v_mov_b32_e32 v57, v157
	v_mul_f32_e32 v0, 0xbfb8aa3b, v50
	v_mul_f32_e32 v50, 0xbfb8aa3b, v51
	v_mul_f32_e32 v51, 0xbfb8aa3b, v52
	v_mul_f32_e32 v52, 0xbfb8aa3b, v53
	v_exp_f32_e32 v0, v0
	v_exp_f32_e32 v50, v50
	v_exp_f32_e32 v51, v51
	v_exp_f32_e32 v52, v52
	v_add_f32_e32 v0, 1.0, v0
	v_add_f32_e32 v62, 1.0, v50
	v_add_f32_e32 v51, 1.0, v51
	v_add_f32_e32 v53, 1.0, v52
	v_rcp_f32_e32 v50, v0
	v_rcp_f32_e32 v52, v51
	v_rcp_f32_e32 v53, v53
	v_rcp_f32_e32 v51, v62
	s_and_b64 vcc, exec, s[0:1]
	s_mov_b64 s[12:13], -1
	v_pk_fma_f32 v[52:53], v[52:53], v[112:113], v[56:57]
	v_pk_fma_f32 v[50:51], v[50:51], v[110:111], v[54:55]
	s_cbranch_vccnz .LBB0_2561
	s_load_dwordx2 s[12:13], s[2:3], 0xd8
	s_waitcnt lgkmcnt(0)
	v_lshl_add_u64 v[54:55], v[138:139], 2, s[12:13]
	v_lshl_add_u64 v[54:55], v[126:127], 2, v[54:55]
	s_mov_b64 s[12:13], 0
	global_store_dwordx4 v[54:55], v[50:53], off offset:192 nt

.LBB0_2563:
	s_nop 1
	v_or_b32_e32 v52, 16, v128
	v_ashrrev_i32_e32 v53, 31, v52
	v_lshlrev_b64 v[50:51], 12, v[52:53]
	v_lshl_add_u64 v[50:51], v[130:131], 0, v[50:51]
	s_nop 3
	v_mov_b32_e32 v54, v158
	v_mov_b32_e32 v55, v159
	v_mov_b32_e32 v56, v160
	v_mov_b32_e32 v57, v161
	v_mul_f32_e32 v0, 0xbfb8aa3b, v46
	v_mul_f32_e32 v46, 0xbfb8aa3b, v47
	v_mul_f32_e32 v47, 0xbfb8aa3b, v48
	v_mul_f32_e32 v48, 0xbfb8aa3b, v49
	v_exp_f32_e32 v0, v0
	v_exp_f32_e32 v46, v46
	v_exp_f32_e32 v47, v47
	v_exp_f32_e32 v48, v48
	v_add_f32_e32 v0, 1.0, v0
	v_add_f32_e32 v62, 1.0, v46
	v_add_f32_e32 v47, 1.0, v47
	v_add_f32_e32 v49, 1.0, v48
	v_rcp_f32_e32 v46, v0
	v_rcp_f32_e32 v48, v47
	v_rcp_f32_e32 v49, v49
	v_rcp_f32_e32 v47, v62
	s_and_b64 vcc, exec, s[0:1]
	v_lshlrev_b64 v[52:53], 10, v[52:53]
	s_mov_b64 s[12:13], -1
	v_pk_fma_f32 v[48:49], v[48:49], v[108:109], v[56:57]
	v_pk_fma_f32 v[46:47], v[46:47], v[106:107], v[54:55]
	s_cbranch_vccnz .LBB0_2565
	s_load_dwordx2 s[12:13], s[2:3], 0xd8
	s_waitcnt lgkmcnt(0)
	v_lshl_add_u64 v[54:55], v[52:53], 2, s[12:13]
	v_lshl_add_u64 v[54:55], v[126:127], 2, v[54:55]
	s_mov_b64 s[12:13], 0
	global_store_dwordx4 v[54:55], v[46:49], off nt

.LBB0_2567:
	s_nop 3
	v_mov_b32_e32 v46, v162
	v_mov_b32_e32 v47, v163
	v_mov_b32_e32 v48, v164
	v_mov_b32_e32 v49, v165
	v_mul_f32_e32 v0, 0xbfb8aa3b, v42
	v_mul_f32_e32 v42, 0xbfb8aa3b, v43
	v_mul_f32_e32 v43, 0xbfb8aa3b, v44
	v_mul_f32_e32 v44, 0xbfb8aa3b, v45
	v_exp_f32_e32 v0, v0
	v_exp_f32_e32 v42, v42
	v_exp_f32_e32 v43, v43
	v_exp_f32_e32 v44, v44
	v_add_f32_e32 v0, 1.0, v0
	v_add_f32_e32 v54, 1.0, v42
	v_add_f32_e32 v43, 1.0, v43
	v_add_f32_e32 v45, 1.0, v44
	v_rcp_f32_e32 v42, v0
	v_rcp_f32_e32 v44, v43
	v_rcp_f32_e32 v45, v45
	v_rcp_f32_e32 v43, v54
	s_and_b64 vcc, exec, s[0:1]
	s_mov_b64 s[12:13], -1
	v_pk_fma_f32 v[44:45], v[44:45], v[104:105], v[48:49]
	v_pk_fma_f32 v[42:43], v[42:43], v[102:103], v[46:47]
	s_cbranch_vccnz .LBB0_2569
	s_load_dwordx2 s[12:13], s[2:3], 0xd8
	s_waitcnt lgkmcnt(0)
	v_lshl_add_u64 v[46:47], v[52:53], 2, s[12:13]
	v_lshl_add_u64 v[46:47], v[126:127], 2, v[46:47]
	s_mov_b64 s[12:13], 0
	global_store_dwordx4 v[46:47], v[42:45], off offset:64 nt

.LBB0_2571:
	s_nop 3
	v_mov_b32_e32 v42, v166
	v_mov_b32_e32 v43, v167
	v_mov_b32_e32 v44, v168
	v_mov_b32_e32 v45, v169
	v_mul_f32_e32 v0, 0xbfb8aa3b, v38
	v_mul_f32_e32 v38, 0xbfb8aa3b, v39
	v_mul_f32_e32 v39, 0xbfb8aa3b, v40
	v_mul_f32_e32 v40, 0xbfb8aa3b, v41
	v_exp_f32_e32 v0, v0
	v_exp_f32_e32 v38, v38
	v_exp_f32_e32 v39, v39
	v_exp_f32_e32 v40, v40
	v_add_f32_e32 v0, 1.0, v0
	v_add_f32_e32 v46, 1.0, v38
	v_add_f32_e32 v39, 1.0, v39
	v_add_f32_e32 v41, 1.0, v40
	v_rcp_f32_e32 v38, v0
	v_rcp_f32_e32 v40, v39
	v_rcp_f32_e32 v41, v41
	v_rcp_f32_e32 v39, v46
	s_and_b64 vcc, exec, s[0:1]
	s_mov_b64 s[12:13], -1
	v_pk_fma_f32 v[40:41], v[40:41], v[100:101], v[44:45]
	v_pk_fma_f32 v[38:39], v[38:39], v[98:99], v[42:43]
	s_cbranch_vccnz .LBB0_2573
	s_load_dwordx2 s[12:13], s[2:3], 0xd8
	s_waitcnt lgkmcnt(0)
	v_lshl_add_u64 v[42:43], v[52:53], 2, s[12:13]
	v_lshl_add_u64 v[42:43], v[126:127], 2, v[42:43]
	s_mov_b64 s[12:13], 0
	global_store_dwordx4 v[42:43], v[38:41], off offset:128 nt

.LBB0_2575:
	s_nop 3
	v_mov_b32_e32 v38, v174
	v_mov_b32_e32 v39, v175
	v_mov_b32_e32 v40, v176
	v_mov_b32_e32 v41, v177
	v_mul_f32_e32 v0, 0xbfb8aa3b, v34
	v_mul_f32_e32 v34, 0xbfb8aa3b, v35
	v_mul_f32_e32 v35, 0xbfb8aa3b, v36
	v_mul_f32_e32 v36, 0xbfb8aa3b, v37
	v_exp_f32_e32 v0, v0
	v_exp_f32_e32 v34, v34
	v_exp_f32_e32 v35, v35
	v_exp_f32_e32 v36, v36
	v_add_f32_e32 v0, 1.0, v0
	v_add_f32_e32 v42, 1.0, v34
	v_add_f32_e32 v35, 1.0, v35
	v_add_f32_e32 v37, 1.0, v36
	v_rcp_f32_e32 v34, v0
	v_rcp_f32_e32 v36, v35
	v_rcp_f32_e32 v37, v37
	v_rcp_f32_e32 v35, v42
	s_and_b64 vcc, exec, s[0:1]
	s_mov_b64 s[12:13], -1
	v_pk_fma_f32 v[36:37], v[36:37], v[96:97], v[40:41]
	v_pk_fma_f32 v[34:35], v[34:35], v[94:95], v[38:39]
	s_cbranch_vccnz .LBB0_2577
	s_load_dwordx2 s[12:13], s[2:3], 0xd8
	s_waitcnt lgkmcnt(0)
	v_lshl_add_u64 v[38:39], v[52:53], 2, s[12:13]
	v_lshl_add_u64 v[38:39], v[126:127], 2, v[38:39]
	s_mov_b64 s[12:13], 0
	global_store_dwordx4 v[38:39], v[34:37], off offset:192 nt

.LBB0_2579:
	s_nop 1
	v_or_b32_e32 v36, 32, v128
	v_ashrrev_i32_e32 v37, 31, v36
	v_lshlrev_b64 v[34:35], 12, v[36:37]
	v_lshl_add_u64 v[34:35], v[130:131], 0, v[34:35]
	s_nop 3
	v_mov_b32_e32 v38, v182
	v_mov_b32_e32 v39, v183
	v_mov_b32_e32 v40, v184
	v_mov_b32_e32 v41, v185
	v_mul_f32_e32 v0, 0xbfb8aa3b, v30
	v_mul_f32_e32 v30, 0xbfb8aa3b, v31
	v_mul_f32_e32 v31, 0xbfb8aa3b, v32
	v_mul_f32_e32 v32, 0xbfb8aa3b, v33
	v_exp_f32_e32 v0, v0
	v_exp_f32_e32 v30, v30
	v_exp_f32_e32 v31, v31
	v_exp_f32_e32 v32, v32
	v_add_f32_e32 v0, 1.0, v0
	v_add_f32_e32 v42, 1.0, v30
	v_add_f32_e32 v31, 1.0, v31
	v_add_f32_e32 v33, 1.0, v32
	v_rcp_f32_e32 v30, v0
	v_rcp_f32_e32 v32, v31
	v_rcp_f32_e32 v33, v33
	v_rcp_f32_e32 v31, v42
	s_and_b64 vcc, exec, s[0:1]
	v_lshlrev_b64 v[36:37], 10, v[36:37]
	s_mov_b64 s[12:13], -1
	v_pk_fma_f32 v[32:33], v[32:33], v[92:93], v[40:41]
	v_pk_fma_f32 v[30:31], v[30:31], v[90:91], v[38:39]
	s_cbranch_vccnz .LBB0_2581
	s_load_dwordx2 s[12:13], s[2:3], 0xd8
	s_waitcnt lgkmcnt(0)
	v_lshl_add_u64 v[38:39], v[36:37], 2, s[12:13]
	v_lshl_add_u64 v[38:39], v[126:127], 2, v[38:39]
	s_mov_b64 s[12:13], 0
	global_store_dwordx4 v[38:39], v[30:33], off nt

.LBB0_2583:
	s_nop 3
	v_mov_b32_e32 v30, v188
	v_mov_b32_e32 v31, v189
	v_mov_b32_e32 v32, v190
	v_mov_b32_e32 v33, v191
	v_mul_f32_e32 v0, 0xbfb8aa3b, v26
	v_mul_f32_e32 v26, 0xbfb8aa3b, v27
	v_mul_f32_e32 v27, 0xbfb8aa3b, v28
	v_mul_f32_e32 v28, 0xbfb8aa3b, v29
	v_exp_f32_e32 v0, v0
	v_exp_f32_e32 v26, v26
	v_exp_f32_e32 v27, v27
	v_exp_f32_e32 v28, v28
	v_add_f32_e32 v0, 1.0, v0
	v_add_f32_e32 v38, 1.0, v26
	v_add_f32_e32 v27, 1.0, v27
	v_add_f32_e32 v29, 1.0, v28
	v_rcp_f32_e32 v26, v0
	v_rcp_f32_e32 v28, v27
	v_rcp_f32_e32 v29, v29
	v_rcp_f32_e32 v27, v38
	s_and_b64 vcc, exec, s[0:1]
	s_mov_b64 s[12:13], -1
	v_pk_fma_f32 v[28:29], v[28:29], v[88:89], v[32:33]
	v_pk_fma_f32 v[26:27], v[26:27], v[86:87], v[30:31]
	s_cbranch_vccnz .LBB0_2585
	s_load_dwordx2 s[12:13], s[2:3], 0xd8
	s_waitcnt lgkmcnt(0)
	v_lshl_add_u64 v[30:31], v[36:37], 2, s[12:13]
	v_lshl_add_u64 v[30:31], v[126:127], 2, v[30:31]
	s_mov_b64 s[12:13], 0
	global_store_dwordx4 v[30:31], v[26:29], off offset:64 nt

.LBB0_2587:
	s_nop 3
	v_mov_b32_e32 v26, v192
	v_mov_b32_e32 v27, v193
	v_mov_b32_e32 v28, v194
	v_mov_b32_e32 v29, v195
	v_mul_f32_e32 v0, 0xbfb8aa3b, v22
	v_mul_f32_e32 v22, 0xbfb8aa3b, v23
	v_mul_f32_e32 v23, 0xbfb8aa3b, v24
	v_mul_f32_e32 v24, 0xbfb8aa3b, v25
	v_exp_f32_e32 v0, v0
	v_exp_f32_e32 v22, v22
	v_exp_f32_e32 v23, v23
	v_exp_f32_e32 v24, v24
	v_add_f32_e32 v0, 1.0, v0
	v_add_f32_e32 v30, 1.0, v22
	v_add_f32_e32 v23, 1.0, v23
	v_add_f32_e32 v25, 1.0, v24
	v_rcp_f32_e32 v22, v0
	v_rcp_f32_e32 v24, v23
	v_rcp_f32_e32 v25, v25
	v_rcp_f32_e32 v23, v30
	s_and_b64 vcc, exec, s[0:1]
	s_mov_b64 s[12:13], -1
	v_pk_fma_f32 v[24:25], v[24:25], v[84:85], v[28:29]
	v_pk_fma_f32 v[22:23], v[22:23], v[82:83], v[26:27]
	s_cbranch_vccnz .LBB0_2589
	s_load_dwordx2 s[12:13], s[2:3], 0xd8
	s_waitcnt lgkmcnt(0)
	v_lshl_add_u64 v[26:27], v[36:37], 2, s[12:13]
	v_lshl_add_u64 v[26:27], v[126:127], 2, v[26:27]
	s_mov_b64 s[12:13], 0
	global_store_dwordx4 v[26:27], v[22:25], off offset:128 nt

.LBB0_2591:
	s_nop 3
	v_mov_b32_e32 v22, v206
	v_mov_b32_e32 v23, v207
	v_mov_b32_e32 v24, v208
	v_mov_b32_e32 v25, v209
	v_mul_f32_e32 v0, 0xbfb8aa3b, v18
	v_mul_f32_e32 v18, 0xbfb8aa3b, v19
	v_mul_f32_e32 v19, 0xbfb8aa3b, v20
	v_mul_f32_e32 v20, 0xbfb8aa3b, v21
	v_exp_f32_e32 v0, v0
	v_exp_f32_e32 v18, v18
	v_exp_f32_e32 v19, v19
	v_exp_f32_e32 v20, v20
	v_add_f32_e32 v0, 1.0, v0
	v_add_f32_e32 v26, 1.0, v18
	v_add_f32_e32 v19, 1.0, v19
	v_add_f32_e32 v21, 1.0, v20
	v_rcp_f32_e32 v18, v0
	v_rcp_f32_e32 v20, v19
	v_rcp_f32_e32 v21, v21
	v_rcp_f32_e32 v19, v26
	s_and_b64 vcc, exec, s[0:1]
	s_mov_b64 s[12:13], -1
	v_pk_fma_f32 v[20:21], v[20:21], v[80:81], v[24:25]
	v_pk_fma_f32 v[18:19], v[18:19], v[78:79], v[22:23]
	s_cbranch_vccnz .LBB0_2593
	s_load_dwordx2 s[12:13], s[2:3], 0xd8
	s_waitcnt lgkmcnt(0)
	v_lshl_add_u64 v[22:23], v[36:37], 2, s[12:13]
	v_lshl_add_u64 v[22:23], v[126:127], 2, v[22:23]
	s_mov_b64 s[12:13], 0
	global_store_dwordx4 v[22:23], v[18:21], off offset:192 nt

.LBB0_2595:
	s_nop 1
	v_or_b32_e32 v20, 48, v128
	v_ashrrev_i32_e32 v21, 31, v20
	v_lshlrev_b64 v[18:19], 12, v[20:21]
	v_lshl_add_u64 v[18:19], v[130:131], 0, v[18:19]
	s_nop 3
	v_mov_b32_e32 v22, v214
	v_mov_b32_e32 v23, v215
	v_mov_b32_e32 v24, v216
	v_mov_b32_e32 v25, v217
	v_mul_f32_e32 v0, 0xbfb8aa3b, v14
	v_mul_f32_e32 v14, 0xbfb8aa3b, v15
	v_mul_f32_e32 v15, 0xbfb8aa3b, v16
	v_mul_f32_e32 v16, 0xbfb8aa3b, v17
	v_exp_f32_e32 v0, v0
	v_exp_f32_e32 v14, v14
	v_exp_f32_e32 v15, v15
	v_exp_f32_e32 v16, v16
	v_add_f32_e32 v0, 1.0, v0
	v_add_f32_e32 v26, 1.0, v14
	v_add_f32_e32 v15, 1.0, v15
	v_add_f32_e32 v17, 1.0, v16
	v_rcp_f32_e32 v14, v0
	v_rcp_f32_e32 v16, v15
	v_rcp_f32_e32 v17, v17
	v_rcp_f32_e32 v15, v26
	s_and_b64 vcc, exec, s[0:1]
	v_lshlrev_b64 v[20:21], 10, v[20:21]
	s_mov_b64 s[12:13], -1
	v_pk_fma_f32 v[16:17], v[16:17], v[76:77], v[24:25]
	v_pk_fma_f32 v[14:15], v[14:15], v[74:75], v[22:23]
	s_cbranch_vccnz .LBB0_2597
	s_load_dwordx2 s[12:13], s[2:3], 0xd8
	s_waitcnt lgkmcnt(0)
	v_lshl_add_u64 v[22:23], v[20:21], 2, s[12:13]
	v_lshl_add_u64 v[22:23], v[126:127], 2, v[22:23]
	s_mov_b64 s[12:13], 0
	global_store_dwordx4 v[22:23], v[14:17], off nt

.LBB0_2599:
	s_nop 3
	v_mov_b32_e32 v14, v218
	v_mov_b32_e32 v15, v219
	v_mov_b32_e32 v16, v220
	v_mov_b32_e32 v17, v221
	v_mul_f32_e32 v0, 0xbfb8aa3b, v10
	v_mul_f32_e32 v10, 0xbfb8aa3b, v11
	v_mul_f32_e32 v11, 0xbfb8aa3b, v12
	v_mul_f32_e32 v12, 0xbfb8aa3b, v13
	v_exp_f32_e32 v0, v0
	v_exp_f32_e32 v10, v10
	v_exp_f32_e32 v11, v11
	v_exp_f32_e32 v12, v12
	v_add_f32_e32 v0, 1.0, v0
	v_add_f32_e32 v22, 1.0, v10
	v_add_f32_e32 v11, 1.0, v11
	v_add_f32_e32 v13, 1.0, v12
	v_rcp_f32_e32 v10, v0
	v_rcp_f32_e32 v12, v11
	v_rcp_f32_e32 v13, v13
	v_rcp_f32_e32 v11, v22
	s_and_b64 vcc, exec, s[0:1]
	s_mov_b64 s[12:13], -1
	v_pk_fma_f32 v[12:13], v[12:13], v[72:73], v[16:17]
	v_pk_fma_f32 v[10:11], v[10:11], v[70:71], v[14:15]
	s_cbranch_vccnz .LBB0_2601
	s_load_dwordx2 s[12:13], s[2:3], 0xd8
	s_waitcnt lgkmcnt(0)
	v_lshl_add_u64 v[14:15], v[20:21], 2, s[12:13]
	v_lshl_add_u64 v[14:15], v[126:127], 2, v[14:15]
	s_mov_b64 s[12:13], 0
	global_store_dwordx4 v[14:15], v[10:13], off offset:64 nt

.LBB0_2603:
	s_nop 3
	v_mov_b32_e32 v10, v242
	v_mov_b32_e32 v11, v243
	v_mov_b32_e32 v12, v244
	v_mov_b32_e32 v13, v245
	v_mul_f32_e32 v0, 0xbfb8aa3b, v6
	v_mul_f32_e32 v6, 0xbfb8aa3b, v7
	v_mul_f32_e32 v7, 0xbfb8aa3b, v8
	v_mul_f32_e32 v8, 0xbfb8aa3b, v9
	v_exp_f32_e32 v0, v0
	v_exp_f32_e32 v6, v6
	v_exp_f32_e32 v7, v7
	v_exp_f32_e32 v8, v8
	v_add_f32_e32 v0, 1.0, v0
	v_add_f32_e32 v14, 1.0, v6
	v_add_f32_e32 v7, 1.0, v7
	v_add_f32_e32 v9, 1.0, v8
	v_rcp_f32_e32 v6, v0
	v_rcp_f32_e32 v8, v7
	v_rcp_f32_e32 v9, v9
	v_rcp_f32_e32 v7, v14
	s_and_b64 vcc, exec, s[0:1]
	s_mov_b64 s[12:13], -1
	v_pk_fma_f32 v[8:9], v[8:9], v[68:69], v[12:13]
	v_pk_fma_f32 v[6:7], v[6:7], v[66:67], v[10:11]
	s_cbranch_vccnz .LBB0_2605
	s_load_dwordx2 s[12:13], s[2:3], 0xd8
	s_waitcnt lgkmcnt(0)
	v_lshl_add_u64 v[10:11], v[20:21], 2, s[12:13]
	v_lshl_add_u64 v[10:11], v[126:127], 2, v[10:11]
	s_mov_b64 s[12:13], 0
	global_store_dwordx4 v[10:11], v[6:9], off offset:128 nt
